# stack11 with the XCD leader's L1 invalidate moved off its arrival path (issued behind the release atomics instead of in front of the L2 write-back)
# speedup vs baseline: 1.0105x; 1.0105x over previous
.LBB0_80:
	s_or_b64 exec, exec, s[12:13]
	v_cvt_f32_u32_e32 v5, v3
	s_waitcnt vmcnt(0)
	v_readfirstlane_b32 s10, v4
	s_add_u32 s8, s8, 0x2400
	s_addc_u32 s9, s9, 0
	v_add_u32_e32 v6, s10, v2
	v_add_u32_e32 v4, 1, v6
	v_mul_u32_u24_e32 v3, 1, v3
	v_mov_b32_e32 v2, 0
	v_cmp_ne_u32_e32 vcc, v4, v3
	s_and_saveexec_b64 s[10:11], vcc
	s_xor_b64 s[10:11], exec, s[10:11]
	s_cbranch_execz .LBB0_94
	buffer_inv sc1
	s_waitcnt lgkmcnt(0)
	v_mov_b32_e32 v1, 0
	global_load_dword v3, v1, s[8:9] sc1
	s_waitcnt vmcnt(0)
	v_cmp_eq_u32_e32 vcc, v3, v2
	s_and_saveexec_b64 s[12:13], vcc
	s_cbranch_execz .LBB0_93
	s_mov_b32 s24, 1
	s_mov_b64 s[14:15], 0
	s_branch .LBB0_84

.LBB0_113:
	s_or_b64 exec, exec, s[10:11]
	buffer_inv sc1
	s_waitcnt vmcnt(0)

.LBB0_174:
	s_or_b64 exec, exec, s[12:13]
	v_cvt_f32_u32_e32 v5, v3
	s_waitcnt vmcnt(0)
	v_readfirstlane_b32 s10, v4
	s_add_u32 s8, s8, 0x2400
	s_addc_u32 s9, s9, 0
	v_add_u32_e32 v6, s10, v2
	v_add_u32_e32 v4, 1, v6
	v_mul_u32_u24_e32 v3, 2, v3
	v_mov_b32_e32 v2, 1
	v_cmp_ne_u32_e32 vcc, v4, v3
	s_and_saveexec_b64 s[10:11], vcc
	s_xor_b64 s[10:11], exec, s[10:11]
	s_cbranch_execz .LBB0_188
	buffer_inv sc1
	s_waitcnt lgkmcnt(0)
	v_mov_b32_e32 v1, 0
	global_load_dword v3, v1, s[8:9] sc1
	s_waitcnt vmcnt(0)
	v_cmp_eq_u32_e32 vcc, v3, v2
	s_and_saveexec_b64 s[12:13], vcc
	s_cbranch_execz .LBB0_187
	s_mov_b32 s24, 1
	s_mov_b64 s[14:15], 0
	s_branch .LBB0_178

.LBB0_271:
	s_or_b64 exec, exec, s[12:13]
	v_cvt_f32_u32_e32 v5, v3
	s_waitcnt vmcnt(0)
	v_readfirstlane_b32 s10, v4
	s_add_u32 s8, s8, 0x2400
	s_addc_u32 s9, s9, 0
	v_add_u32_e32 v6, s10, v2
	v_add_u32_e32 v4, 1, v6
	v_mul_u32_u24_e32 v3, 3, v3
	v_mov_b32_e32 v2, 2
	v_cmp_ne_u32_e32 vcc, v4, v3
	s_and_saveexec_b64 s[10:11], vcc
	s_xor_b64 s[10:11], exec, s[10:11]
	s_cbranch_execz .LBB0_285
	buffer_inv sc1
	s_waitcnt lgkmcnt(0)
	v_mov_b32_e32 v1, 0
	global_load_dword v3, v1, s[8:9] sc1
	s_waitcnt vmcnt(0)
	v_cmp_eq_u32_e32 vcc, v3, v2
	s_and_saveexec_b64 s[12:13], vcc
	s_cbranch_execz .LBB0_284
	s_mov_b32 s24, 1
	s_mov_b64 s[14:15], 0
	s_branch .LBB0_275

.LBB0_343:
	s_or_b64 exec, exec, s[12:13]
	v_cvt_f32_u32_e32 v5, v3
	s_waitcnt vmcnt(0)
	v_readfirstlane_b32 s10, v4
	s_add_u32 s8, s8, 0x2400
	s_addc_u32 s9, s9, 0
	v_add_u32_e32 v6, s10, v2
	v_add_u32_e32 v4, 1, v6
	v_mul_u32_u24_e32 v3, 4, v3
	v_mov_b32_e32 v2, 3
	v_cmp_ne_u32_e32 vcc, v4, v3
	s_and_saveexec_b64 s[10:11], vcc
	s_xor_b64 s[10:11], exec, s[10:11]
	s_cbranch_execz .LBB0_357
	buffer_inv sc1
	s_waitcnt lgkmcnt(0)
	v_mov_b32_e32 v1, 0
	global_load_dword v3, v1, s[8:9] sc1
	s_waitcnt vmcnt(0)
	v_cmp_eq_u32_e32 vcc, v3, v2
	s_and_saveexec_b64 s[12:13], vcc
	s_cbranch_execz .LBB0_356
	s_mov_b32 s24, 1
	s_mov_b64 s[14:15], 0
	s_branch .LBB0_347

.LBB0_442:
	s_or_b64 exec, exec, s[12:13]
	v_cvt_f32_u32_e32 v5, v3
	s_waitcnt vmcnt(0)
	v_readfirstlane_b32 s10, v4
	s_add_u32 s8, s8, 0x2400
	s_addc_u32 s9, s9, 0
	v_add_u32_e32 v6, s10, v2
	v_add_u32_e32 v4, 1, v6
	v_mul_u32_u24_e32 v3, 5, v3
	v_mov_b32_e32 v2, 4
	v_cmp_ne_u32_e32 vcc, v4, v3
	s_and_saveexec_b64 s[10:11], vcc
	s_xor_b64 s[10:11], exec, s[10:11]
	s_cbranch_execz .LBB0_456
	buffer_inv sc1
	s_waitcnt lgkmcnt(0)
	v_mov_b32_e32 v1, 0
	global_load_dword v3, v1, s[8:9] sc1
	s_waitcnt vmcnt(0)
	v_cmp_eq_u32_e32 vcc, v3, v2
	s_and_saveexec_b64 s[12:13], vcc
	s_cbranch_execz .LBB0_455
	s_mov_b32 s24, 1
	s_mov_b64 s[14:15], 0
	s_branch .LBB0_446

.LBB0_519:
	s_or_b64 exec, exec, s[12:13]
	v_cvt_f32_u32_e32 v5, v3
	s_waitcnt vmcnt(0)
	v_readfirstlane_b32 s10, v4
	s_add_u32 s8, s8, 0x2400
	s_addc_u32 s9, s9, 0
	v_add_u32_e32 v6, s10, v2
	v_add_u32_e32 v4, 1, v6
	v_mul_u32_u24_e32 v3, 6, v3
	v_mov_b32_e32 v2, 5
	v_cmp_ne_u32_e32 vcc, v4, v3
	s_and_saveexec_b64 s[10:11], vcc
	s_xor_b64 s[10:11], exec, s[10:11]
	s_cbranch_execz .LBB0_533
	buffer_inv sc1
	s_waitcnt lgkmcnt(0)
	v_mov_b32_e32 v1, 0
	global_load_dword v3, v1, s[8:9] sc1
	s_waitcnt vmcnt(0)
	v_cmp_eq_u32_e32 vcc, v3, v2
	s_and_saveexec_b64 s[12:13], vcc
	s_cbranch_execz .LBB0_532
	s_mov_b32 s24, 1
	s_mov_b64 s[14:15], 0
	s_branch .LBB0_523

.LBB0_600:
	s_or_b64 exec, exec, s[12:13]
	v_cvt_f32_u32_e32 v5, v3
	s_waitcnt vmcnt(0)
	v_readfirstlane_b32 s10, v4
	s_add_u32 s8, s8, 0x2400
	s_addc_u32 s9, s9, 0
	v_add_u32_e32 v6, s10, v2
	v_add_u32_e32 v4, 1, v6
	v_mul_u32_u24_e32 v3, 7, v3
	v_mov_b32_e32 v2, 6
	v_cmp_ne_u32_e32 vcc, v4, v3
	s_and_saveexec_b64 s[10:11], vcc
	s_xor_b64 s[10:11], exec, s[10:11]
	s_cbranch_execz .LBB0_614
	buffer_inv sc1
	s_waitcnt lgkmcnt(0)
	v_mov_b32_e32 v1, 0
	global_load_dword v3, v1, s[8:9] sc1
	s_waitcnt vmcnt(0)
	v_cmp_eq_u32_e32 vcc, v3, v2
	s_and_saveexec_b64 s[12:13], vcc
	s_cbranch_execz .LBB0_613
	s_mov_b32 s24, 1
	s_mov_b64 s[14:15], 0
	s_branch .LBB0_604

.LBB0_680:
	s_or_b64 exec, exec, s[12:13]
	v_cvt_f32_u32_e32 v5, v3
	s_waitcnt vmcnt(0)
	v_readfirstlane_b32 s10, v4
	s_add_u32 s8, s8, 0x2400
	s_addc_u32 s9, s9, 0
	v_add_u32_e32 v6, s10, v2
	v_add_u32_e32 v4, 1, v6
	v_mul_u32_u24_e32 v3, 8, v3
	v_mov_b32_e32 v2, 7
	v_cmp_ne_u32_e32 vcc, v4, v3
	s_and_saveexec_b64 s[10:11], vcc
	s_xor_b64 s[10:11], exec, s[10:11]
	s_cbranch_execz .LBB0_694
	buffer_inv sc1
	s_waitcnt lgkmcnt(0)
	v_mov_b32_e32 v1, 0
	global_load_dword v3, v1, s[8:9] sc1
	s_waitcnt vmcnt(0)
	v_cmp_eq_u32_e32 vcc, v3, v2
	s_and_saveexec_b64 s[12:13], vcc
	s_cbranch_execz .LBB0_693
	s_mov_b32 s24, 1
	s_mov_b64 s[14:15], 0
	s_branch .LBB0_684

.LBB0_774:
	s_or_b64 exec, exec, s[12:13]
	v_cvt_f32_u32_e32 v5, v3
	s_waitcnt vmcnt(0)
	v_readfirstlane_b32 s10, v4
	s_add_u32 s8, s8, 0x2400
	s_addc_u32 s9, s9, 0
	v_add_u32_e32 v6, s10, v2
	v_add_u32_e32 v4, 1, v6
	v_mul_u32_u24_e32 v3, 9, v3
	v_mov_b32_e32 v2, 8
	v_cmp_ne_u32_e32 vcc, v4, v3
	s_and_saveexec_b64 s[10:11], vcc
	s_xor_b64 s[10:11], exec, s[10:11]
	s_cbranch_execz .LBB0_788
	buffer_inv sc1
	s_waitcnt lgkmcnt(0)
	v_mov_b32_e32 v1, 0
	global_load_dword v3, v1, s[8:9] sc1
	s_waitcnt vmcnt(0)
	v_cmp_eq_u32_e32 vcc, v3, v2
	s_and_saveexec_b64 s[12:13], vcc
	s_cbranch_execz .LBB0_787
	s_mov_b32 s24, 1
	s_mov_b64 s[14:15], 0
	s_branch .LBB0_778

.LBB0_871:
	s_or_b64 exec, exec, s[12:13]
	v_cvt_f32_u32_e32 v5, v3
	s_waitcnt vmcnt(0)
	v_readfirstlane_b32 s10, v4
	s_add_u32 s8, s8, 0x2400
	s_addc_u32 s9, s9, 0
	v_add_u32_e32 v6, s10, v2
	v_add_u32_e32 v4, 1, v6
	v_mul_u32_u24_e32 v3, 10, v3
	v_mov_b32_e32 v2, 9
	v_cmp_ne_u32_e32 vcc, v4, v3
	s_and_saveexec_b64 s[10:11], vcc
	s_xor_b64 s[10:11], exec, s[10:11]
	s_cbranch_execz .LBB0_885
	buffer_inv sc1
	s_waitcnt lgkmcnt(0)
	v_mov_b32_e32 v1, 0
	global_load_dword v3, v1, s[8:9] sc1
	s_waitcnt vmcnt(0)
	v_cmp_eq_u32_e32 vcc, v3, v2
	s_and_saveexec_b64 s[12:13], vcc
	s_cbranch_execz .LBB0_884
	s_mov_b32 s24, 1
	s_mov_b64 s[14:15], 0
	s_branch .LBB0_875

.LBB0_951:
	s_or_b64 exec, exec, s[12:13]
	v_cvt_f32_u32_e32 v5, v3
	s_waitcnt vmcnt(0)
	v_readfirstlane_b32 s10, v4
	s_add_u32 s8, s8, 0x2400
	s_addc_u32 s9, s9, 0
	v_add_u32_e32 v6, s10, v2
	v_add_u32_e32 v4, 1, v6
	v_mul_u32_u24_e32 v3, 11, v3
	v_mov_b32_e32 v2, 10
	v_cmp_ne_u32_e32 vcc, v4, v3
	s_and_saveexec_b64 s[10:11], vcc
	s_xor_b64 s[10:11], exec, s[10:11]
	s_cbranch_execz .LBB0_965
	buffer_inv sc1
	s_waitcnt lgkmcnt(0)
	v_mov_b32_e32 v1, 0
	global_load_dword v3, v1, s[8:9] sc1
	s_waitcnt vmcnt(0)
	v_cmp_eq_u32_e32 vcc, v3, v2
	s_and_saveexec_b64 s[12:13], vcc
	s_cbranch_execz .LBB0_964
	s_mov_b32 s24, 1
	s_mov_b64 s[14:15], 0
	s_branch .LBB0_955

.LBB0_1045:
	s_or_b64 exec, exec, s[12:13]
	v_cvt_f32_u32_e32 v5, v3
	s_waitcnt vmcnt(0)
	v_readfirstlane_b32 s10, v4
	s_add_u32 s8, s8, 0x2400
	s_addc_u32 s9, s9, 0
	v_add_u32_e32 v6, s10, v2
	v_add_u32_e32 v4, 1, v6
	v_mul_u32_u24_e32 v3, 12, v3
	v_mov_b32_e32 v2, 11
	v_cmp_ne_u32_e32 vcc, v4, v3
	s_and_saveexec_b64 s[10:11], vcc
	s_xor_b64 s[10:11], exec, s[10:11]
	s_cbranch_execz .LBB0_1059
	buffer_inv sc1
	s_waitcnt lgkmcnt(0)
	v_mov_b32_e32 v1, 0
	global_load_dword v3, v1, s[8:9] sc1
	s_waitcnt vmcnt(0)
	v_cmp_eq_u32_e32 vcc, v3, v2
	s_and_saveexec_b64 s[12:13], vcc
	s_cbranch_execz .LBB0_1058
	s_mov_b32 s24, 1
	s_mov_b64 s[14:15], 0
	s_branch .LBB0_1049

.LBB0_1142:
	s_or_b64 exec, exec, s[12:13]
	v_cvt_f32_u32_e32 v5, v3
	s_waitcnt vmcnt(0)
	v_readfirstlane_b32 s10, v4
	s_add_u32 s8, s8, 0x2400
	s_addc_u32 s9, s9, 0
	v_add_u32_e32 v6, s10, v2
	v_add_u32_e32 v4, 1, v6
	v_mul_u32_u24_e32 v3, 13, v3
	v_mov_b32_e32 v2, 12
	v_cmp_ne_u32_e32 vcc, v4, v3
	s_and_saveexec_b64 s[10:11], vcc
	s_xor_b64 s[10:11], exec, s[10:11]
	s_cbranch_execz .LBB0_1156
	buffer_inv sc1
	s_waitcnt lgkmcnt(0)
	v_mov_b32_e32 v1, 0
	global_load_dword v3, v1, s[8:9] sc1
	s_waitcnt vmcnt(0)
	v_cmp_eq_u32_e32 vcc, v3, v2
	s_and_saveexec_b64 s[12:13], vcc
	s_cbranch_execz .LBB0_1155
	s_mov_b32 s24, 1
	s_mov_b64 s[14:15], 0
	s_branch .LBB0_1146

.LBB0_1214:
	s_or_b64 exec, exec, s[12:13]
	v_cvt_f32_u32_e32 v5, v3
	s_waitcnt vmcnt(0)
	v_readfirstlane_b32 s10, v4
	s_add_u32 s8, s8, 0x2400
	s_addc_u32 s9, s9, 0
	v_add_u32_e32 v6, s10, v2
	v_add_u32_e32 v4, 1, v6
	v_mul_u32_u24_e32 v3, 14, v3
	v_mov_b32_e32 v2, 13
	v_cmp_ne_u32_e32 vcc, v4, v3
	s_and_saveexec_b64 s[10:11], vcc
	s_xor_b64 s[10:11], exec, s[10:11]
	s_cbranch_execz .LBB0_1228
	buffer_inv sc1
	s_waitcnt lgkmcnt(0)
	v_mov_b32_e32 v1, 0
	global_load_dword v3, v1, s[8:9] sc1
	s_waitcnt vmcnt(0)
	v_cmp_eq_u32_e32 vcc, v3, v2
	s_and_saveexec_b64 s[12:13], vcc
	s_cbranch_execz .LBB0_1227
	s_mov_b32 s24, 1
	s_mov_b64 s[14:15], 0
	s_branch .LBB0_1218

.LBB0_1291:
	s_or_b64 exec, exec, s[12:13]
	v_cvt_f32_u32_e32 v5, v3
	s_waitcnt vmcnt(0)
	v_readfirstlane_b32 s10, v4
	s_add_u32 s8, s8, 0x2400
	s_addc_u32 s9, s9, 0
	v_add_u32_e32 v6, s10, v2
	v_add_u32_e32 v4, 1, v6
	v_mul_u32_u24_e32 v3, 15, v3
	v_mov_b32_e32 v2, 14
	v_cmp_ne_u32_e32 vcc, v4, v3
	s_and_saveexec_b64 s[10:11], vcc
	s_xor_b64 s[10:11], exec, s[10:11]
	s_cbranch_execz .LBB0_1305
	buffer_inv sc1
	s_waitcnt lgkmcnt(0)
	v_mov_b32_e32 v1, 0
	global_load_dword v3, v1, s[8:9] sc1
	s_waitcnt vmcnt(0)
	v_cmp_eq_u32_e32 vcc, v3, v2
	s_and_saveexec_b64 s[12:13], vcc
	s_cbranch_execz .LBB0_1304
	s_mov_b32 s24, 1
	s_mov_b64 s[14:15], 0
	s_branch .LBB0_1295

.LBB0_1377:
	s_or_b64 exec, exec, s[12:13]
	v_cvt_f32_u32_e32 v5, v3
	s_waitcnt vmcnt(0)
	v_readfirstlane_b32 s10, v4
	s_add_u32 s8, s8, 0x2400
	s_addc_u32 s9, s9, 0
	v_add_u32_e32 v6, s10, v2
	v_add_u32_e32 v4, 1, v6
	v_mul_u32_u24_e32 v3, 16, v3
	v_mov_b32_e32 v2, 15
	v_cmp_ne_u32_e32 vcc, v4, v3
	s_and_saveexec_b64 s[10:11], vcc
	s_xor_b64 s[10:11], exec, s[10:11]
	s_cbranch_execz .LBB0_1391
	buffer_inv sc1
	s_waitcnt lgkmcnt(0)
	v_mov_b32_e32 v1, 0
	global_load_dword v3, v1, s[8:9] sc1
	s_waitcnt vmcnt(0)
	v_cmp_eq_u32_e32 vcc, v3, v2
	s_and_saveexec_b64 s[12:13], vcc
	s_cbranch_execz .LBB0_1390
	s_mov_b32 s26, 1
	s_mov_b64 s[14:15], 0
	s_branch .LBB0_1381

.LBB0_1458:
	s_or_b64 exec, exec, s[12:13]
	v_cvt_f32_u32_e32 v5, v3
	s_waitcnt vmcnt(0)
	v_readfirstlane_b32 s10, v4
	s_add_u32 s8, s8, 0x2400
	s_addc_u32 s9, s9, 0
	v_add_u32_e32 v6, s10, v2
	v_add_u32_e32 v4, 1, v6
	v_mul_u32_u24_e32 v3, 17, v3
	v_mov_b32_e32 v2, 16
	v_cmp_ne_u32_e32 vcc, v4, v3
	s_and_saveexec_b64 s[10:11], vcc
	s_xor_b64 s[10:11], exec, s[10:11]
	s_cbranch_execz .LBB0_1472
	buffer_inv sc1
	s_waitcnt lgkmcnt(0)
	v_mov_b32_e32 v1, 0
	global_load_dword v3, v1, s[8:9] sc1
	s_waitcnt vmcnt(0)
	v_cmp_eq_u32_e32 vcc, v3, v2
	s_and_saveexec_b64 s[12:13], vcc
	s_cbranch_execz .LBB0_1471
	s_mov_b32 s26, 1
	s_mov_b64 s[14:15], 0
	s_branch .LBB0_1462

.LBB0_1538:
	s_or_b64 exec, exec, s[12:13]
	v_cvt_f32_u32_e32 v5, v3
	s_waitcnt vmcnt(0)
	v_readfirstlane_b32 s10, v4
	s_add_u32 s8, s8, 0x2400
	s_addc_u32 s9, s9, 0
	v_add_u32_e32 v6, s10, v2
	v_add_u32_e32 v4, 1, v6
	v_mul_u32_u24_e32 v3, 18, v3
	v_mov_b32_e32 v2, 17
	v_cmp_ne_u32_e32 vcc, v4, v3
	s_and_saveexec_b64 s[10:11], vcc
	s_xor_b64 s[10:11], exec, s[10:11]
	s_cbranch_execz .LBB0_1552
	buffer_inv sc1
	s_waitcnt lgkmcnt(0)
	v_mov_b32_e32 v1, 0
	global_load_dword v3, v1, s[8:9] sc1
	s_waitcnt vmcnt(0)
	v_cmp_eq_u32_e32 vcc, v3, v2
	s_and_saveexec_b64 s[12:13], vcc
	s_cbranch_execz .LBB0_1551
	s_mov_b32 s26, 1
	s_mov_b64 s[14:15], 0
	s_branch .LBB0_1542

.LBB0_1632:
	s_or_b64 exec, exec, s[12:13]
	v_cvt_f32_u32_e32 v5, v3
	s_waitcnt vmcnt(0)
	v_readfirstlane_b32 s10, v4
	s_add_u32 s8, s8, 0x2400
	s_addc_u32 s9, s9, 0
	v_add_u32_e32 v6, s10, v2
	v_add_u32_e32 v4, 1, v6
	v_mul_u32_u24_e32 v3, 19, v3
	v_mov_b32_e32 v2, 18
	v_cmp_ne_u32_e32 vcc, v4, v3
	s_and_saveexec_b64 s[10:11], vcc
	s_xor_b64 s[10:11], exec, s[10:11]
	s_cbranch_execz .LBB0_1646
	buffer_inv sc1
	s_waitcnt lgkmcnt(0)
	v_mov_b32_e32 v1, 0
	global_load_dword v3, v1, s[8:9] sc1
	s_waitcnt vmcnt(0)
	v_cmp_eq_u32_e32 vcc, v3, v2
	s_and_saveexec_b64 s[12:13], vcc
	s_cbranch_execz .LBB0_1645
	s_mov_b32 s26, 1
	s_mov_b64 s[14:15], 0
	s_branch .LBB0_1636

.LBB0_1729:
	s_or_b64 exec, exec, s[12:13]
	v_cvt_f32_u32_e32 v5, v3
	s_waitcnt vmcnt(0)
	v_readfirstlane_b32 s10, v4
	s_add_u32 s8, s8, 0x2400
	s_addc_u32 s9, s9, 0
	v_add_u32_e32 v6, s10, v2
	v_add_u32_e32 v4, 1, v6
	v_mul_u32_u24_e32 v3, 20, v3
	v_mov_b32_e32 v2, 19
	v_cmp_ne_u32_e32 vcc, v4, v3
	s_and_saveexec_b64 s[10:11], vcc
	s_xor_b64 s[10:11], exec, s[10:11]
	s_cbranch_execz .LBB0_1743
	buffer_inv sc1
	s_waitcnt lgkmcnt(0)
	v_mov_b32_e32 v1, 0
	global_load_dword v3, v1, s[8:9] sc1
	s_waitcnt vmcnt(0)
	v_cmp_eq_u32_e32 vcc, v3, v2
	s_and_saveexec_b64 s[12:13], vcc
	s_cbranch_execz .LBB0_1742
	s_mov_b32 s26, 1
	s_mov_b64 s[14:15], 0
	s_branch .LBB0_1733

.LBB0_1809:
	s_or_b64 exec, exec, s[12:13]
	v_cvt_f32_u32_e32 v5, v3
	s_waitcnt vmcnt(0)
	v_readfirstlane_b32 s10, v4
	s_add_u32 s8, s8, 0x2400
	s_addc_u32 s9, s9, 0
	v_add_u32_e32 v6, s10, v2
	v_add_u32_e32 v4, 1, v6
	v_mul_u32_u24_e32 v3, 21, v3
	v_mov_b32_e32 v2, 20
	v_cmp_ne_u32_e32 vcc, v4, v3
	s_and_saveexec_b64 s[10:11], vcc
	s_xor_b64 s[10:11], exec, s[10:11]
	s_cbranch_execz .LBB0_1823
	buffer_inv sc1
	s_waitcnt lgkmcnt(0)
	v_mov_b32_e32 v1, 0
	global_load_dword v3, v1, s[8:9] sc1
	s_waitcnt vmcnt(0)
	v_cmp_eq_u32_e32 vcc, v3, v2
	s_and_saveexec_b64 s[12:13], vcc
	s_cbranch_execz .LBB0_1822
	s_mov_b32 s26, 1
	s_mov_b64 s[14:15], 0
	s_branch .LBB0_1813

.LBB0_1903:
	s_or_b64 exec, exec, s[12:13]
	v_cvt_f32_u32_e32 v5, v3
	s_waitcnt vmcnt(0)
	v_readfirstlane_b32 s10, v4
	s_add_u32 s8, s8, 0x2400
	s_addc_u32 s9, s9, 0
	v_add_u32_e32 v6, s10, v2
	v_add_u32_e32 v4, 1, v6
	v_mul_u32_u24_e32 v3, 22, v3
	v_mov_b32_e32 v2, 21
	v_cmp_ne_u32_e32 vcc, v4, v3
	s_and_saveexec_b64 s[10:11], vcc
	s_xor_b64 s[10:11], exec, s[10:11]
	s_cbranch_execz .LBB0_1917
	buffer_inv sc1
	s_waitcnt lgkmcnt(0)
	v_mov_b32_e32 v1, 0
	global_load_dword v3, v1, s[8:9] sc1
	s_waitcnt vmcnt(0)
	v_cmp_eq_u32_e32 vcc, v3, v2
	s_and_saveexec_b64 s[12:13], vcc
	s_cbranch_execz .LBB0_1916
	s_mov_b32 s26, 1
	s_mov_b64 s[14:15], 0
	s_branch .LBB0_1907

.LBB0_2000:
	s_or_b64 exec, exec, s[12:13]
	v_cvt_f32_u32_e32 v5, v3
	s_waitcnt vmcnt(0)
	v_readfirstlane_b32 s10, v4
	s_add_u32 s8, s8, 0x2400
	s_addc_u32 s9, s9, 0
	v_add_u32_e32 v6, s10, v2
	v_add_u32_e32 v4, 1, v6
	v_mul_u32_u24_e32 v3, 23, v3
	v_mov_b32_e32 v2, 22
	v_cmp_ne_u32_e32 vcc, v4, v3
	s_and_saveexec_b64 s[10:11], vcc
	s_xor_b64 s[10:11], exec, s[10:11]
	s_cbranch_execz .LBB0_2014
	buffer_inv sc1
	s_waitcnt lgkmcnt(0)
	v_mov_b32_e32 v1, 0
	global_load_dword v3, v1, s[8:9] sc1
	s_waitcnt vmcnt(0)
	v_cmp_eq_u32_e32 vcc, v3, v2
	s_and_saveexec_b64 s[12:13], vcc
	s_cbranch_execz .LBB0_2013
	s_mov_b32 s26, 1
	s_mov_b64 s[14:15], 0
	s_branch .LBB0_2004

.LBB0_2072:
	s_or_b64 exec, exec, s[12:13]
	v_cvt_f32_u32_e32 v5, v3
	s_waitcnt vmcnt(0)
	v_readfirstlane_b32 s10, v4
	s_add_u32 s8, s8, 0x2400
	s_addc_u32 s9, s9, 0
	v_add_u32_e32 v6, s10, v2
	v_add_u32_e32 v4, 1, v6
	v_mul_u32_u24_e32 v3, 24, v3
	v_mov_b32_e32 v2, 23
	v_cmp_ne_u32_e32 vcc, v4, v3
	s_and_saveexec_b64 s[10:11], vcc
	s_xor_b64 s[10:11], exec, s[10:11]
	s_cbranch_execz .LBB0_2086
	buffer_inv sc1
	s_waitcnt lgkmcnt(0)
	v_mov_b32_e32 v1, 0
	global_load_dword v3, v1, s[8:9] sc1
	s_waitcnt vmcnt(0)
	v_cmp_eq_u32_e32 vcc, v3, v2
	s_and_saveexec_b64 s[12:13], vcc
	s_cbranch_execz .LBB0_2085
	s_mov_b32 s26, 1
	s_mov_b64 s[14:15], 0
	s_branch .LBB0_2076

.LBB0_2252:
	s_or_b64 exec, exec, s[10:11]
	v_cvt_f32_u32_e32 v5, v3
	s_waitcnt vmcnt(0)
	v_readfirstlane_b32 s8, v4
	s_add_u32 s6, s6, 0x2400
	s_addc_u32 s7, s7, 0
	v_add_u32_e32 v6, s8, v2
	v_add_u32_e32 v4, 1, v6
	v_mul_u32_u24_e32 v3, 25, v3
	v_mov_b32_e32 v2, 24
	v_cmp_ne_u32_e32 vcc, v4, v3
	s_and_saveexec_b64 s[8:9], vcc
	s_xor_b64 s[8:9], exec, s[8:9]
	s_cbranch_execz .LBB0_2266
	buffer_inv sc1
	s_waitcnt lgkmcnt(0)
	v_mov_b32_e32 v1, 0
	global_load_dword v3, v1, s[6:7] sc1
	s_waitcnt vmcnt(0)
	v_cmp_eq_u32_e32 vcc, v3, v2
	s_and_saveexec_b64 s[10:11], vcc
	s_cbranch_execz .LBB0_2265
	s_mov_b32 s24, 1
	s_mov_b64 s[12:13], 0
	s_branch .LBB0_2256

.LBB0_2285:
	s_or_b64 exec, exec, s[8:9]
	buffer_inv sc1
	s_waitcnt vmcnt(0)

.LBB0_2333:
	s_or_b64 exec, exec, s[10:11]
	v_cvt_f32_u32_e32 v5, v3
	s_waitcnt vmcnt(0)
	v_readfirstlane_b32 s8, v4
	s_add_u32 s6, s6, 0x2400
	s_addc_u32 s7, s7, 0
	v_add_u32_e32 v6, s8, v2
	v_add_u32_e32 v4, 1, v6
	v_mul_u32_u24_e32 v3, 26, v3
	v_mov_b32_e32 v2, 25
	v_cmp_ne_u32_e32 vcc, v4, v3
	s_and_saveexec_b64 s[8:9], vcc
	s_xor_b64 s[8:9], exec, s[8:9]
	s_cbranch_execz .LBB0_2347
	buffer_inv sc1
	s_waitcnt lgkmcnt(0)
	v_mov_b32_e32 v1, 0
	global_load_dword v3, v1, s[6:7] sc1
	s_waitcnt vmcnt(0)
	v_cmp_eq_u32_e32 vcc, v3, v2
	s_and_saveexec_b64 s[10:11], vcc
	s_cbranch_execz .LBB0_2346
	s_mov_b32 s24, 1
	s_mov_b64 s[12:13], 0
	s_branch .LBB0_2337

.LBB0_2413:
	s_or_b64 exec, exec, s[10:11]
	v_cvt_f32_u32_e32 v5, v3
	s_waitcnt vmcnt(0)
	v_readfirstlane_b32 s8, v4
	s_add_u32 s6, s6, 0x2400
	s_addc_u32 s7, s7, 0
	v_add_u32_e32 v6, s8, v2
	v_add_u32_e32 v4, 1, v6
	v_mul_u32_u24_e32 v3, 27, v3
	v_mov_b32_e32 v2, 26
	v_cmp_ne_u32_e32 vcc, v4, v3
	s_and_saveexec_b64 s[8:9], vcc
	s_xor_b64 s[8:9], exec, s[8:9]
	s_cbranch_execz .LBB0_2427
	buffer_inv sc1
	s_waitcnt lgkmcnt(0)
	v_mov_b32_e32 v1, 0
	global_load_dword v3, v1, s[6:7] sc1
	s_waitcnt vmcnt(0)
	v_cmp_eq_u32_e32 vcc, v3, v2
	s_and_saveexec_b64 s[10:11], vcc
	s_cbranch_execz .LBB0_2426
	s_mov_b32 s24, 1
	s_mov_b64 s[12:13], 0
	s_branch .LBB0_2417

.LBB0_2507:
	s_or_b64 exec, exec, s[10:11]
	v_cvt_f32_u32_e32 v5, v3
	s_waitcnt vmcnt(0)
	v_readfirstlane_b32 s8, v4
	s_add_u32 s6, s6, 0x2400
	s_addc_u32 s7, s7, 0
	v_add_u32_e32 v6, s8, v2
	v_add_u32_e32 v4, 1, v6
	v_mul_u32_u24_e32 v3, 28, v3
	v_mov_b32_e32 v2, 27
	v_cmp_ne_u32_e32 vcc, v4, v3
	s_and_saveexec_b64 s[8:9], vcc
	s_xor_b64 s[8:9], exec, s[8:9]
	s_cbranch_execz .LBB0_2521
	buffer_inv sc1
	s_waitcnt lgkmcnt(0)
	v_mov_b32_e32 v1, 0
	global_load_dword v3, v1, s[6:7] sc1
	s_waitcnt vmcnt(0)
	v_cmp_eq_u32_e32 vcc, v3, v2
	s_and_saveexec_b64 s[10:11], vcc
	s_cbranch_execz .LBB0_2520
	s_mov_b32 s24, 1
	s_mov_b64 s[12:13], 0
	s_branch .LBB0_2511

.LBB0_2604:
	s_or_b64 exec, exec, s[10:11]
	v_cvt_f32_u32_e32 v5, v3
	s_waitcnt vmcnt(0)
	v_readfirstlane_b32 s8, v4
	s_add_u32 s6, s6, 0x2400
	s_addc_u32 s7, s7, 0
	v_add_u32_e32 v6, s8, v2
	v_add_u32_e32 v4, 1, v6
	v_mul_u32_u24_e32 v3, 29, v3
	v_mov_b32_e32 v2, 28
	v_cmp_ne_u32_e32 vcc, v4, v3
	s_and_saveexec_b64 s[8:9], vcc
	s_xor_b64 s[8:9], exec, s[8:9]
	s_cbranch_execz .LBB0_2618
	buffer_inv sc1
	s_waitcnt lgkmcnt(0)
	v_mov_b32_e32 v1, 0
	global_load_dword v3, v1, s[6:7] sc1
	s_waitcnt vmcnt(0)
	v_cmp_eq_u32_e32 vcc, v3, v2
	s_and_saveexec_b64 s[10:11], vcc
	s_cbranch_execz .LBB0_2617
	s_mov_b32 s24, 1
	s_mov_b64 s[12:13], 0
	s_branch .LBB0_2608

.LBB0_2684:
	s_or_b64 exec, exec, s[10:11]
	v_cvt_f32_u32_e32 v5, v3
	s_waitcnt vmcnt(0)
	v_readfirstlane_b32 s8, v4
	s_add_u32 s6, s6, 0x2400
	s_addc_u32 s7, s7, 0
	v_add_u32_e32 v6, s8, v2
	v_add_u32_e32 v4, 1, v6
	v_mul_u32_u24_e32 v3, 30, v3
	v_mov_b32_e32 v2, 29
	v_cmp_ne_u32_e32 vcc, v4, v3
	s_and_saveexec_b64 s[8:9], vcc
	s_xor_b64 s[8:9], exec, s[8:9]
	s_cbranch_execz .LBB0_2698
	buffer_inv sc1
	s_waitcnt lgkmcnt(0)
	v_mov_b32_e32 v1, 0
	global_load_dword v3, v1, s[6:7] sc1
	s_waitcnt vmcnt(0)
	v_cmp_eq_u32_e32 vcc, v3, v2
	s_and_saveexec_b64 s[10:11], vcc
	s_cbranch_execz .LBB0_2697
	s_mov_b32 s24, 1
	s_mov_b64 s[12:13], 0
	s_branch .LBB0_2688

.LBB0_2778:
	s_or_b64 exec, exec, s[10:11]
	v_cvt_f32_u32_e32 v5, v3
	s_waitcnt vmcnt(0)
	v_readfirstlane_b32 s8, v4
	s_add_u32 s6, s6, 0x2400
	s_addc_u32 s7, s7, 0
	v_add_u32_e32 v6, s8, v2
	v_add_u32_e32 v4, 1, v6
	v_mul_u32_u24_e32 v3, 31, v3
	v_mov_b32_e32 v2, 30
	v_cmp_ne_u32_e32 vcc, v4, v3
	s_and_saveexec_b64 s[8:9], vcc
	s_xor_b64 s[8:9], exec, s[8:9]
	s_cbranch_execz .LBB0_2792
	buffer_inv sc1
	s_waitcnt lgkmcnt(0)
	v_mov_b32_e32 v1, 0
	global_load_dword v3, v1, s[6:7] sc1
	s_waitcnt vmcnt(0)
	v_cmp_eq_u32_e32 vcc, v3, v2
	s_and_saveexec_b64 s[10:11], vcc
	s_cbranch_execz .LBB0_2791
	s_mov_b32 s24, 1
	s_mov_b64 s[12:13], 0
	s_branch .LBB0_2782

.LBB0_2875:
	s_or_b64 exec, exec, s[10:11]
	v_cvt_f32_u32_e32 v5, v3
	s_waitcnt vmcnt(0)
	v_readfirstlane_b32 s8, v4
	s_add_u32 s6, s6, 0x2400
	s_addc_u32 s7, s7, 0
	v_add_u32_e32 v6, s8, v2
	v_add_u32_e32 v4, 1, v6
	v_mul_u32_u24_e32 v3, 32, v3
	v_mov_b32_e32 v2, 31
	v_cmp_ne_u32_e32 vcc, v4, v3
	s_and_saveexec_b64 s[8:9], vcc
	s_xor_b64 s[8:9], exec, s[8:9]
	s_cbranch_execz .LBB0_2889
	buffer_inv sc1
	s_waitcnt lgkmcnt(0)
	v_mov_b32_e32 v1, 0
	global_load_dword v3, v1, s[6:7] sc1
	s_waitcnt vmcnt(0)
	v_cmp_eq_u32_e32 vcc, v3, v2
	s_and_saveexec_b64 s[10:11], vcc
	s_cbranch_execz .LBB0_2888
	s_mov_b32 s24, 1
	s_mov_b64 s[12:13], 0
	s_branch .LBB0_2879

.LBB0_2947:
	s_or_b64 exec, exec, s[10:11]
	v_cvt_f32_u32_e32 v5, v3
	s_waitcnt vmcnt(0)
	v_readfirstlane_b32 s8, v4
	s_add_u32 s6, s6, 0x2400
	s_addc_u32 s7, s7, 0
	v_add_u32_e32 v6, s8, v2
	v_add_u32_e32 v4, 1, v6
	v_mul_u32_u24_e32 v3, 33, v3
	v_mov_b32_e32 v2, 32
	v_cmp_ne_u32_e32 vcc, v4, v3
	s_and_saveexec_b64 s[8:9], vcc
	s_xor_b64 s[8:9], exec, s[8:9]
	s_cbranch_execz .LBB0_2961
	buffer_inv sc1
	s_waitcnt lgkmcnt(0)
	v_mov_b32_e32 v1, 0
	global_load_dword v3, v1, s[6:7] sc1
	s_waitcnt vmcnt(0)
	v_cmp_eq_u32_e32 vcc, v3, v2
	s_and_saveexec_b64 s[10:11], vcc
	s_cbranch_execz .LBB0_2960
	s_mov_b32 s24, 1
	s_mov_b64 s[12:13], 0
	s_branch .LBB0_2951

.LBB0_3045:
	s_or_b64 exec, exec, s[10:11]
	v_cvt_f32_u32_e32 v5, v3
	s_waitcnt vmcnt(0)
	v_readfirstlane_b32 s8, v4
	s_add_u32 s6, s6, 0x2400
	s_addc_u32 s7, s7, 0
	v_add_u32_e32 v6, s8, v2
	v_add_u32_e32 v4, 1, v6
	v_mul_u32_u24_e32 v3, 34, v3
	v_mov_b32_e32 v2, 33
	v_cmp_ne_u32_e32 vcc, v4, v3
	s_and_saveexec_b64 s[8:9], vcc
	s_xor_b64 s[8:9], exec, s[8:9]
	s_cbranch_execz .LBB0_3059
	buffer_inv sc1
	s_waitcnt lgkmcnt(0)
	v_mov_b32_e32 v1, 0
	global_load_dword v3, v1, s[6:7] sc1
	s_waitcnt vmcnt(0)
	v_cmp_eq_u32_e32 vcc, v3, v2
	s_and_saveexec_b64 s[10:11], vcc
	s_cbranch_execz .LBB0_3058
	s_mov_b32 s24, 1
	s_mov_b64 s[12:13], 0
	s_branch .LBB0_3049

.LBB0_3108:
	s_or_b64 exec, exec, s[10:11]
	v_cvt_f32_u32_e32 v5, v3
	s_waitcnt vmcnt(0)
	v_readfirstlane_b32 s8, v4
	s_add_u32 s6, s6, 0x2400
	s_addc_u32 s7, s7, 0
	v_add_u32_e32 v6, s8, v2
	v_add_u32_e32 v4, 1, v6
	v_mul_u32_u24_e32 v3, 35, v3
	v_mov_b32_e32 v2, 34
	v_cmp_ne_u32_e32 vcc, v4, v3
	s_and_saveexec_b64 s[8:9], vcc
	s_xor_b64 s[8:9], exec, s[8:9]
	s_cbranch_execz .LBB0_3122
	buffer_inv sc1
	s_waitcnt lgkmcnt(0)
	v_mov_b32_e32 v1, 0
	global_load_dword v3, v1, s[6:7] sc1
	s_waitcnt vmcnt(0)
	v_cmp_eq_u32_e32 vcc, v3, v2
	s_and_saveexec_b64 s[10:11], vcc
	s_cbranch_execz .LBB0_3121
	s_mov_b32 s24, 1
	s_mov_b64 s[12:13], 0
	s_branch .LBB0_3112

.LBB0_3169:
	s_or_b64 exec, exec, s[10:11]
	v_cvt_f32_u32_e32 v5, v3
	s_waitcnt vmcnt(0)
	v_readfirstlane_b32 s8, v4
	s_add_u32 s6, s6, 0x2400
	s_addc_u32 s7, s7, 0
	v_add_u32_e32 v6, s8, v2
	v_add_u32_e32 v4, 1, v6
	v_mul_u32_u24_e32 v3, 36, v3
	v_mov_b32_e32 v2, 35
	v_cmp_ne_u32_e32 vcc, v4, v3
	s_and_saveexec_b64 s[8:9], vcc
	s_xor_b64 s[8:9], exec, s[8:9]
	s_cbranch_execz .LBB0_3183
	buffer_inv sc1
	s_waitcnt lgkmcnt(0)
	v_mov_b32_e32 v1, 0
	global_load_dword v3, v1, s[6:7] sc1
	s_waitcnt vmcnt(0)
	v_cmp_eq_u32_e32 vcc, v3, v2
	s_and_saveexec_b64 s[10:11], vcc
	s_cbranch_execz .LBB0_3182
	s_mov_b32 s22, 1
	s_mov_b64 s[12:13], 0
	s_branch .LBB0_3173

.LBB0_3250:
	s_or_b64 exec, exec, s[10:11]
	v_cvt_f32_u32_e32 v5, v3
	s_waitcnt vmcnt(0)
	v_readfirstlane_b32 s8, v4
	s_add_u32 s6, s6, 0x2400
	s_addc_u32 s7, s7, 0
	v_add_u32_e32 v6, s8, v2
	v_add_u32_e32 v4, 1, v6
	v_mul_u32_u24_e32 v3, 37, v3
	v_mov_b32_e32 v2, 36
	v_cmp_ne_u32_e32 vcc, v4, v3
	s_and_saveexec_b64 s[8:9], vcc
	s_xor_b64 s[8:9], exec, s[8:9]
	s_cbranch_execz .LBB0_3264
	buffer_inv sc1
	s_waitcnt lgkmcnt(0)
	v_mov_b32_e32 v1, 0
	global_load_dword v3, v1, s[6:7] sc1
	s_waitcnt vmcnt(0)
	v_cmp_eq_u32_e32 vcc, v3, v2
	s_and_saveexec_b64 s[10:11], vcc
	s_cbranch_execz .LBB0_3263
	s_mov_b32 s22, 1
	s_mov_b64 s[12:13], 0
	s_branch .LBB0_3254

.LBB0_3330:
	s_or_b64 exec, exec, s[10:11]
	v_cvt_f32_u32_e32 v5, v3
	s_waitcnt vmcnt(0)
	v_readfirstlane_b32 s8, v4
	s_add_u32 s6, s6, 0x2400
	s_addc_u32 s7, s7, 0
	v_add_u32_e32 v6, s8, v2
	v_add_u32_e32 v4, 1, v6
	v_mul_u32_u24_e32 v3, 38, v3
	v_mov_b32_e32 v2, 37
	v_cmp_ne_u32_e32 vcc, v4, v3
	s_and_saveexec_b64 s[8:9], vcc
	s_xor_b64 s[8:9], exec, s[8:9]
	s_cbranch_execz .LBB0_3344
	buffer_inv sc1
	s_waitcnt lgkmcnt(0)
	v_mov_b32_e32 v1, 0
	global_load_dword v3, v1, s[6:7] sc1
	s_waitcnt vmcnt(0)
	v_cmp_eq_u32_e32 vcc, v3, v2
	s_and_saveexec_b64 s[10:11], vcc
	s_cbranch_execz .LBB0_3343
	s_mov_b32 s22, 1
	s_mov_b64 s[12:13], 0
	s_branch .LBB0_3334

.LBB0_3424:
	s_or_b64 exec, exec, s[10:11]
	v_cvt_f32_u32_e32 v5, v3
	s_waitcnt vmcnt(0)
	v_readfirstlane_b32 s3, v4
	s_add_u32 s6, s6, 0x2400
	s_addc_u32 s7, s7, 0
	v_add_u32_e32 v6, s3, v2
	v_add_u32_e32 v4, 1, v6
	v_mul_u32_u24_e32 v3, 39, v3
	v_mov_b32_e32 v2, 38
	v_cmp_ne_u32_e32 vcc, v4, v3
	s_and_saveexec_b64 s[8:9], vcc
	s_xor_b64 s[8:9], exec, s[8:9]
	s_cbranch_execz .LBB0_3438
	buffer_inv sc1
	s_waitcnt lgkmcnt(0)
	v_mov_b32_e32 v1, 0
	global_load_dword v3, v1, s[6:7] sc1
	s_waitcnt vmcnt(0)
	v_cmp_eq_u32_e32 vcc, v3, v2
	s_and_saveexec_b64 s[10:11], vcc
	s_cbranch_execz .LBB0_3437
	s_mov_b32 s3, 1
	s_mov_b64 s[12:13], 0
	s_branch .LBB0_3428

.LBB0_3522:
	s_or_b64 exec, exec, s[8:9]
	v_cvt_f32_u32_e32 v5, v3
	s_waitcnt vmcnt(0)
	v_readfirstlane_b32 s6, v4
	s_add_u32 s4, s4, 0x2400
	s_addc_u32 s5, s5, 0
	v_add_u32_e32 v6, s6, v2
	v_add_u32_e32 v4, 1, v6
	v_mul_u32_u24_e32 v3, 40, v3
	v_mov_b32_e32 v2, 39
	v_cmp_ne_u32_e32 vcc, v4, v3
	s_and_saveexec_b64 s[6:7], vcc
	s_xor_b64 s[6:7], exec, s[6:7]
	s_cbranch_execz .LBB0_3536
	buffer_inv sc1
	s_waitcnt lgkmcnt(0)
	v_mov_b32_e32 v1, 0
	global_load_dword v3, v1, s[4:5] sc1
	s_waitcnt vmcnt(0)
	v_cmp_eq_u32_e32 vcc, v3, v2
	s_and_saveexec_b64 s[8:9], vcc
	s_cbranch_execz .LBB0_3535
	s_mov_b32 s20, 1
	s_mov_b64 s[10:11], 0
	s_branch .LBB0_3526

.LBB0_3555:
	s_or_b64 exec, exec, s[6:7]
	buffer_inv sc1
	s_waitcnt vmcnt(0)

.LBB0_3592:
	s_or_b64 exec, exec, s[8:9]
	v_cvt_f32_u32_e32 v4, v2
	s_waitcnt vmcnt(0)
	v_readfirstlane_b32 s6, v3
	s_add_u32 s4, s4, 0x2400
	s_addc_u32 s5, s5, 0
	v_add_u32_e32 v5, s6, v1
	v_add_u32_e32 v3, 1, v5
	v_mul_u32_u24_e32 v2, 41, v2
	v_mov_b32_e32 v1, 40
	v_cmp_ne_u32_e32 vcc, v3, v2
	s_and_saveexec_b64 s[6:7], vcc
	s_xor_b64 s[6:7], exec, s[6:7]
	s_cbranch_execz .LBB0_3606
	buffer_inv sc1
	s_waitcnt lgkmcnt(0)
	v_mov_b32_e32 v0, 0
	global_load_dword v2, v0, s[4:5] sc1
	s_waitcnt vmcnt(0)
	v_cmp_eq_u32_e32 vcc, v2, v1
	s_and_saveexec_b64 s[8:9], vcc
	s_cbranch_execz .LBB0_3605
	s_mov_b32 s20, 1
	s_mov_b64 s[10:11], 0
	s_branch .LBB0_3596
